# static s_setprio 1 for waves 4-7 during the SSD/LRU/HGRN scan phases (two waves per SIMD), reset at the phase exits
# speedup vs baseline: 1.0089x; 1.0044x over previous
; __device__ __forceinline__ void ssd_phase(const Args& A, unsigned char* smem, const bool dry) {
;     ...
;     for (int u = blockIdx.x; u < 256; u += gridDim.x) {
;         const int b = u >> 4, h = u & 15, g = h >> 2;
;         __syncthreads();
.LBB0_415:
	v_readfirstlane_b32 s98, v152
	s_nop 3
	s_cmp_ge_u32 s98, 0x100
	s_cbranch_scc0 .Lsp0_skip
	s_setprio 1

; #define SEAM(k) do { if (COOP && IN(k) && IN((k) + 1)) { if ((k) == 0) { cg::this_grid().sync(); xbar = xcd_barrier_post((unsigned*)(ws + WS_BAR), (volatile LAS unsigned*)(lds + 131072)); } else xcd_barrier(xbar); } } while (0)
; template <bool COOP>
; __global__ void __launch_bounds__(512, 2) mega(Args A) {
;     ...
;     if (IN(3)) { ssd_phase(A, smem, false); lru_phase(A, smem, false); }
;     SEAM(3);
.LBB0_557:
	s_setprio 0
	v_readlane_b32 s40, v251, 54
	v_readlane_b32 s41, v251, 55

; #define SEAM(k) do { if (COOP && IN(k) && IN((k) + 1)) { if ((k) == 0) { cg::this_grid().sync(); xbar = xcd_barrier_post((unsigned*)(ws + WS_BAR), (volatile LAS unsigned*)(lds + 131072)); } else xcd_barrier(xbar); } } while (0)
; template <bool COOP>
; __global__ void __launch_bounds__(512, 2) mega(Args A) {
;     ...
;     if (IN(9)) { hgrn_phase(A, smem, false); }
;     SEAM(9);
.LBB0_991:
	s_setprio 0
	v_readlane_b32 s40, v251, 54
	v_readlane_b32 s41, v251, 55
	v_readlane_b32 s0, v251, 36
	v_readlane_b32 s1, v251, 37
	v_readlane_b32 s2, v251, 38
	v_readlane_b32 s3, v251, 39
	v_readlane_b32 s4, v251, 40
	v_readlane_b32 s5, v251, 41
	v_readlane_b32 s6, v251, 42
	v_readlane_b32 s7, v251, 43
	v_readlane_b32 s8, v251, 44
	v_readlane_b32 s9, v251, 45
	v_readlane_b32 s10, v251, 46
	v_readlane_b32 s11, v251, 47
	v_readlane_b32 s12, v251, 48
	v_readlane_b32 s13, v251, 49
	v_readlane_b32 s14, v251, 50
	v_readlane_b32 s15, v251, 51
